# phase0 mod_partials: DPP row_newbcast FMAs (5 VALU per row instead of 5 readlane + 3 FMA)
# baseline (speedup 1.0000x reference)
.LBB0_21:
	v_readfirstlane_b32 s98, v12
	v_readfirstlane_b32 s99, v13
	v_and_b32_e32 v27, 63, v18
	v_lshlrev_b32_e32 v27, 2, v27
	s_nop 3
	global_load_dword v132, v27, s[98:99] nt
	s_add_u32 s98, s98, 0x3000
	s_addc_u32 s99, s99, 0
	global_load_dword v133, v27, s[98:99] nt
	s_add_u32 s98, s98, 0x3000
	s_addc_u32 s99, s99, 0
	global_load_dword v134, v27, s[98:99] nt
	s_add_u32 s98, s98, 0x3000
	s_addc_u32 s99, s99, 0
	global_load_dword v135, v27, s[98:99] nt
	s_add_u32 s98, s98, 0x3000
	s_addc_u32 s99, s99, 0
	global_load_dword v136, v27, s[98:99] nt
	s_add_u32 s98, s98, 0x3000
	s_addc_u32 s99, s99, 0
	global_load_dword v137, v27, s[98:99] nt
	s_add_u32 s98, s98, 0x3000
	s_addc_u32 s99, s99, 0
	global_load_dword v138, v27, s[98:99] nt
	s_add_u32 s98, s98, 0x3000
	s_addc_u32 s99, s99, 0
	global_load_dword v139, v27, s[98:99] nt
	s_add_u32 s98, s98, 0x3000
	s_addc_u32 s99, s99, 0
	global_load_dword v140, v27, s[98:99] nt
	s_add_u32 s98, s98, 0x3000
	s_addc_u32 s99, s99, 0
	global_load_dword v141, v27, s[98:99] nt
	s_add_u32 s98, s98, 0x3000
	s_addc_u32 s99, s99, 0
	global_load_dword v142, v27, s[98:99] nt
	s_add_u32 s98, s98, 0x3000
	s_addc_u32 s99, s99, 0
	global_load_dword v143, v27, s[98:99] nt
	s_add_u32 s98, s98, 0x3000
	s_addc_u32 s99, s99, 0
	global_load_dword v144, v27, s[98:99] nt
	s_add_u32 s98, s98, 0x3000
	s_addc_u32 s99, s99, 0
	global_load_dword v145, v27, s[98:99] nt
	s_add_u32 s98, s98, 0x3000
	s_addc_u32 s99, s99, 0
	global_load_dword v146, v27, s[98:99] nt
	s_add_u32 s98, s98, 0x3000
	s_addc_u32 s99, s99, 0
	global_load_dword v147, v27, s[98:99] nt
	s_add_u32 s98, s98, 0x3000
	s_addc_u32 s99, s99, 0
	global_load_dword v148, v27, s[98:99] nt
	s_add_u32 s98, s98, 0x3000
	s_addc_u32 s99, s99, 0
	global_load_dword v149, v27, s[98:99] nt
	s_add_u32 s98, s98, 0x3000
	s_addc_u32 s99, s99, 0
	global_load_dword v150, v27, s[98:99] nt
	s_add_u32 s98, s98, 0x3000
	s_addc_u32 s99, s99, 0
	global_load_dword v151, v27, s[98:99] nt
	s_add_u32 s98, s98, 0x3000
	s_addc_u32 s99, s99, 0
	global_load_dword v152, v27, s[98:99] nt
	s_add_u32 s98, s98, 0x3000
	s_addc_u32 s99, s99, 0
	global_load_dword v153, v27, s[98:99] nt
	s_add_u32 s98, s98, 0x3000
	s_addc_u32 s99, s99, 0
	global_load_dword v154, v27, s[98:99] nt
	s_add_u32 s98, s98, 0x3000
	s_addc_u32 s99, s99, 0
	global_load_dword v155, v27, s[98:99] nt
	s_add_u32 s98, s98, 0x3000
	s_addc_u32 s99, s99, 0
	global_load_dword v156, v27, s[98:99] nt
	s_add_u32 s98, s98, 0x3000
	s_addc_u32 s99, s99, 0
	global_load_dword v157, v27, s[98:99] nt
	s_add_u32 s98, s98, 0x3000
	s_addc_u32 s99, s99, 0
	global_load_dword v158, v27, s[98:99] nt
	s_add_u32 s98, s98, 0x3000
	s_addc_u32 s99, s99, 0
	global_load_dword v159, v27, s[98:99] nt
	s_add_u32 s98, s98, 0x3000
	s_addc_u32 s99, s99, 0
	global_load_dword v160, v27, s[98:99] nt
	s_add_u32 s98, s98, 0x3000
	s_addc_u32 s99, s99, 0
	global_load_dword v161, v27, s[98:99] nt
	s_add_u32 s98, s98, 0x3000
	s_addc_u32 s99, s99, 0
	global_load_dword v162, v27, s[98:99] nt
	s_add_u32 s98, s98, 0x3000
	s_addc_u32 s99, s99, 0
	global_load_dword v163, v27, s[98:99] nt
	s_add_u32 s98, s98, 0x3000
	s_addc_u32 s99, s99, 0
	global_load_dword v164, v27, s[98:99] nt
	s_add_u32 s98, s98, 0x3000
	s_addc_u32 s99, s99, 0
	global_load_dword v165, v27, s[98:99] nt
	s_add_u32 s98, s98, 0x3000
	s_addc_u32 s99, s99, 0
	global_load_dword v166, v27, s[98:99] nt
	s_add_u32 s98, s98, 0x3000
	s_addc_u32 s99, s99, 0
	global_load_dword v167, v27, s[98:99] nt
	s_add_u32 s98, s98, 0x3000
	s_addc_u32 s99, s99, 0
	global_load_dword v168, v27, s[98:99] nt
	s_add_u32 s98, s98, 0x3000
	s_addc_u32 s99, s99, 0
	global_load_dword v169, v27, s[98:99] nt
	s_add_u32 s98, s98, 0x3000
	s_addc_u32 s99, s99, 0
	global_load_dword v170, v27, s[98:99] nt
	s_add_u32 s98, s98, 0x3000
	s_addc_u32 s99, s99, 0
	global_load_dword v171, v27, s[98:99] nt
	s_add_u32 s98, s98, 0x3000
	s_addc_u32 s99, s99, 0
	global_load_dword v172, v27, s[98:99] nt
	s_add_u32 s98, s98, 0x3000
	s_addc_u32 s99, s99, 0
	global_load_dword v173, v27, s[98:99] nt
	s_add_u32 s98, s98, 0x3000
	s_addc_u32 s99, s99, 0
	global_load_dword v174, v27, s[98:99] nt
	s_add_u32 s98, s98, 0x3000
	s_addc_u32 s99, s99, 0
	global_load_dword v175, v27, s[98:99] nt
	s_add_u32 s98, s98, 0x3000
	s_addc_u32 s99, s99, 0
	global_load_dword v176, v27, s[98:99] nt
	s_add_u32 s98, s98, 0x3000
	s_addc_u32 s99, s99, 0
	global_load_dword v177, v27, s[98:99] nt
	s_add_u32 s98, s98, 0x3000
	s_addc_u32 s99, s99, 0
	global_load_dword v178, v27, s[98:99] nt
	s_add_u32 s98, s98, 0x3000
	s_addc_u32 s99, s99, 0
	global_load_dword v179, v27, s[98:99] nt
	s_add_u32 s98, s98, 0x3000
	s_addc_u32 s99, s99, 0
	global_load_dword v180, v27, s[98:99] nt
	s_add_u32 s98, s98, 0x3000
	s_addc_u32 s99, s99, 0
	global_load_dword v181, v27, s[98:99] nt
	s_add_u32 s98, s98, 0x3000
	s_addc_u32 s99, s99, 0
	global_load_dword v182, v27, s[98:99] nt
	s_add_u32 s98, s98, 0x3000
	s_addc_u32 s99, s99, 0
	global_load_dword v183, v27, s[98:99] nt
	s_add_u32 s98, s98, 0x3000
	s_addc_u32 s99, s99, 0
	global_load_dword v184, v27, s[98:99] nt
	s_add_u32 s98, s98, 0x3000
	s_addc_u32 s99, s99, 0
	global_load_dword v185, v27, s[98:99] nt
	s_add_u32 s98, s98, 0x3000
	s_addc_u32 s99, s99, 0
	global_load_dword v186, v27, s[98:99] nt
	s_add_u32 s98, s98, 0x3000
	s_addc_u32 s99, s99, 0
	global_load_dword v187, v27, s[98:99] nt
	s_add_u32 s98, s98, 0x3000
	s_addc_u32 s99, s99, 0
	global_load_dword v188, v27, s[98:99] nt
	s_add_u32 s98, s98, 0x3000
	s_addc_u32 s99, s99, 0
	global_load_dword v189, v27, s[98:99] nt
	s_add_u32 s98, s98, 0x3000
	s_addc_u32 s99, s99, 0
	global_load_dword v190, v27, s[98:99] nt
	s_add_u32 s98, s98, 0x3000
	s_addc_u32 s99, s99, 0
	global_load_dword v191, v27, s[98:99] nt
	s_add_u32 s98, s98, 0x3000
	s_addc_u32 s99, s99, 0
	global_load_dword v192, v27, s[98:99] nt
	s_add_u32 s98, s98, 0x3000
	s_addc_u32 s99, s99, 0
	global_load_dword v193, v27, s[98:99] nt
	s_add_u32 s98, s98, 0x3000
	s_addc_u32 s99, s99, 0
	global_load_dword v194, v27, s[98:99] nt
	s_add_u32 s98, s98, 0x3000
	s_addc_u32 s99, s99, 0
	global_load_dword v195, v27, s[98:99] nt
	v_and_b32_e32 v48, 60, v27
	v_add_u32_e32 v49, 64, v48
	v_add_u32_e32 v50, 0x80, v48
	v_add_u32_e32 v51, 0xc0, v48
	ds_bpermute_b32 v28, v48, v0
	ds_bpermute_b32 v29, v49, v0
	ds_bpermute_b32 v30, v50, v0
	ds_bpermute_b32 v31, v51, v0
	ds_bpermute_b32 v32, v48, v23
	ds_bpermute_b32 v33, v49, v23
	ds_bpermute_b32 v34, v50, v23
	ds_bpermute_b32 v35, v51, v23
	ds_bpermute_b32 v36, v48, v24
	ds_bpermute_b32 v37, v49, v24
	ds_bpermute_b32 v38, v50, v24
	ds_bpermute_b32 v39, v51, v24
	ds_bpermute_b32 v40, v48, v25
	ds_bpermute_b32 v41, v49, v25
	ds_bpermute_b32 v42, v50, v25
	ds_bpermute_b32 v43, v51, v25
	ds_bpermute_b32 v44, v48, v26
	ds_bpermute_b32 v45, v49, v26
	ds_bpermute_b32 v46, v50, v26
	ds_bpermute_b32 v47, v51, v26
	s_waitcnt lgkmcnt(0)
	s_waitcnt vmcnt(63)
	v_fmac_f32_dpp v10, v28, v132 row_newbcast:0 row_mask:0xf bank_mask:0xf
	v_fmac_f32_dpp v11, v32, v132 row_newbcast:0 row_mask:0xf bank_mask:0xf
	v_fmac_f32_dpp v8, v36, v132 row_newbcast:0 row_mask:0xf bank_mask:0xf
	v_fmac_f32_dpp v9, v40, v132 row_newbcast:0 row_mask:0xf bank_mask:0xf
	v_fmac_f32_dpp v22, v44, v132 row_newbcast:0 row_mask:0xf bank_mask:0xf
	s_waitcnt vmcnt(62)
	v_fmac_f32_dpp v10, v28, v133 row_newbcast:1 row_mask:0xf bank_mask:0xf
	v_fmac_f32_dpp v11, v32, v133 row_newbcast:1 row_mask:0xf bank_mask:0xf
	v_fmac_f32_dpp v8, v36, v133 row_newbcast:1 row_mask:0xf bank_mask:0xf
	v_fmac_f32_dpp v9, v40, v133 row_newbcast:1 row_mask:0xf bank_mask:0xf
	v_fmac_f32_dpp v22, v44, v133 row_newbcast:1 row_mask:0xf bank_mask:0xf
	s_waitcnt vmcnt(61)
	v_fmac_f32_dpp v10, v28, v134 row_newbcast:2 row_mask:0xf bank_mask:0xf
	v_fmac_f32_dpp v11, v32, v134 row_newbcast:2 row_mask:0xf bank_mask:0xf
	v_fmac_f32_dpp v8, v36, v134 row_newbcast:2 row_mask:0xf bank_mask:0xf
	v_fmac_f32_dpp v9, v40, v134 row_newbcast:2 row_mask:0xf bank_mask:0xf
	v_fmac_f32_dpp v22, v44, v134 row_newbcast:2 row_mask:0xf bank_mask:0xf
	s_waitcnt vmcnt(60)
	v_fmac_f32_dpp v10, v28, v135 row_newbcast:3 row_mask:0xf bank_mask:0xf
	v_fmac_f32_dpp v11, v32, v135 row_newbcast:3 row_mask:0xf bank_mask:0xf
	v_fmac_f32_dpp v8, v36, v135 row_newbcast:3 row_mask:0xf bank_mask:0xf
	v_fmac_f32_dpp v9, v40, v135 row_newbcast:3 row_mask:0xf bank_mask:0xf
	v_fmac_f32_dpp v22, v44, v135 row_newbcast:3 row_mask:0xf bank_mask:0xf
	s_waitcnt vmcnt(59)
	v_fmac_f32_dpp v10, v28, v136 row_newbcast:4 row_mask:0xf bank_mask:0xf
	v_fmac_f32_dpp v11, v32, v136 row_newbcast:4 row_mask:0xf bank_mask:0xf
	v_fmac_f32_dpp v8, v36, v136 row_newbcast:4 row_mask:0xf bank_mask:0xf
	v_fmac_f32_dpp v9, v40, v136 row_newbcast:4 row_mask:0xf bank_mask:0xf
	v_fmac_f32_dpp v22, v44, v136 row_newbcast:4 row_mask:0xf bank_mask:0xf
	s_waitcnt vmcnt(58)
	v_fmac_f32_dpp v10, v28, v137 row_newbcast:5 row_mask:0xf bank_mask:0xf
	v_fmac_f32_dpp v11, v32, v137 row_newbcast:5 row_mask:0xf bank_mask:0xf
	v_fmac_f32_dpp v8, v36, v137 row_newbcast:5 row_mask:0xf bank_mask:0xf
	v_fmac_f32_dpp v9, v40, v137 row_newbcast:5 row_mask:0xf bank_mask:0xf
	v_fmac_f32_dpp v22, v44, v137 row_newbcast:5 row_mask:0xf bank_mask:0xf
	s_waitcnt vmcnt(57)
	v_fmac_f32_dpp v10, v28, v138 row_newbcast:6 row_mask:0xf bank_mask:0xf
	v_fmac_f32_dpp v11, v32, v138 row_newbcast:6 row_mask:0xf bank_mask:0xf
	v_fmac_f32_dpp v8, v36, v138 row_newbcast:6 row_mask:0xf bank_mask:0xf
	v_fmac_f32_dpp v9, v40, v138 row_newbcast:6 row_mask:0xf bank_mask:0xf
	v_fmac_f32_dpp v22, v44, v138 row_newbcast:6 row_mask:0xf bank_mask:0xf
	s_waitcnt vmcnt(56)
	v_fmac_f32_dpp v10, v28, v139 row_newbcast:7 row_mask:0xf bank_mask:0xf
	v_fmac_f32_dpp v11, v32, v139 row_newbcast:7 row_mask:0xf bank_mask:0xf
	v_fmac_f32_dpp v8, v36, v139 row_newbcast:7 row_mask:0xf bank_mask:0xf
	v_fmac_f32_dpp v9, v40, v139 row_newbcast:7 row_mask:0xf bank_mask:0xf
	v_fmac_f32_dpp v22, v44, v139 row_newbcast:7 row_mask:0xf bank_mask:0xf
	s_waitcnt vmcnt(55)
	v_fmac_f32_dpp v10, v28, v140 row_newbcast:8 row_mask:0xf bank_mask:0xf
	v_fmac_f32_dpp v11, v32, v140 row_newbcast:8 row_mask:0xf bank_mask:0xf
	v_fmac_f32_dpp v8, v36, v140 row_newbcast:8 row_mask:0xf bank_mask:0xf
	v_fmac_f32_dpp v9, v40, v140 row_newbcast:8 row_mask:0xf bank_mask:0xf
	v_fmac_f32_dpp v22, v44, v140 row_newbcast:8 row_mask:0xf bank_mask:0xf
	s_waitcnt vmcnt(54)
	v_fmac_f32_dpp v10, v28, v141 row_newbcast:9 row_mask:0xf bank_mask:0xf
	v_fmac_f32_dpp v11, v32, v141 row_newbcast:9 row_mask:0xf bank_mask:0xf
	v_fmac_f32_dpp v8, v36, v141 row_newbcast:9 row_mask:0xf bank_mask:0xf
	v_fmac_f32_dpp v9, v40, v141 row_newbcast:9 row_mask:0xf bank_mask:0xf
	v_fmac_f32_dpp v22, v44, v141 row_newbcast:9 row_mask:0xf bank_mask:0xf
	s_waitcnt vmcnt(53)
	v_fmac_f32_dpp v10, v28, v142 row_newbcast:10 row_mask:0xf bank_mask:0xf
	v_fmac_f32_dpp v11, v32, v142 row_newbcast:10 row_mask:0xf bank_mask:0xf
	v_fmac_f32_dpp v8, v36, v142 row_newbcast:10 row_mask:0xf bank_mask:0xf
	v_fmac_f32_dpp v9, v40, v142 row_newbcast:10 row_mask:0xf bank_mask:0xf
	v_fmac_f32_dpp v22, v44, v142 row_newbcast:10 row_mask:0xf bank_mask:0xf
	s_waitcnt vmcnt(52)
	v_fmac_f32_dpp v10, v28, v143 row_newbcast:11 row_mask:0xf bank_mask:0xf
	v_fmac_f32_dpp v11, v32, v143 row_newbcast:11 row_mask:0xf bank_mask:0xf
	v_fmac_f32_dpp v8, v36, v143 row_newbcast:11 row_mask:0xf bank_mask:0xf
	v_fmac_f32_dpp v9, v40, v143 row_newbcast:11 row_mask:0xf bank_mask:0xf
	v_fmac_f32_dpp v22, v44, v143 row_newbcast:11 row_mask:0xf bank_mask:0xf
	s_waitcnt vmcnt(51)
	v_fmac_f32_dpp v10, v28, v144 row_newbcast:12 row_mask:0xf bank_mask:0xf
	v_fmac_f32_dpp v11, v32, v144 row_newbcast:12 row_mask:0xf bank_mask:0xf
	v_fmac_f32_dpp v8, v36, v144 row_newbcast:12 row_mask:0xf bank_mask:0xf
	v_fmac_f32_dpp v9, v40, v144 row_newbcast:12 row_mask:0xf bank_mask:0xf
	v_fmac_f32_dpp v22, v44, v144 row_newbcast:12 row_mask:0xf bank_mask:0xf
	s_waitcnt vmcnt(50)
	v_fmac_f32_dpp v10, v28, v145 row_newbcast:13 row_mask:0xf bank_mask:0xf
	v_fmac_f32_dpp v11, v32, v145 row_newbcast:13 row_mask:0xf bank_mask:0xf
	v_fmac_f32_dpp v8, v36, v145 row_newbcast:13 row_mask:0xf bank_mask:0xf
	v_fmac_f32_dpp v9, v40, v145 row_newbcast:13 row_mask:0xf bank_mask:0xf
	v_fmac_f32_dpp v22, v44, v145 row_newbcast:13 row_mask:0xf bank_mask:0xf
	s_waitcnt vmcnt(49)
	v_fmac_f32_dpp v10, v28, v146 row_newbcast:14 row_mask:0xf bank_mask:0xf
	v_fmac_f32_dpp v11, v32, v146 row_newbcast:14 row_mask:0xf bank_mask:0xf
	v_fmac_f32_dpp v8, v36, v146 row_newbcast:14 row_mask:0xf bank_mask:0xf
	v_fmac_f32_dpp v9, v40, v146 row_newbcast:14 row_mask:0xf bank_mask:0xf
	v_fmac_f32_dpp v22, v44, v146 row_newbcast:14 row_mask:0xf bank_mask:0xf
	s_waitcnt vmcnt(48)
	v_fmac_f32_dpp v10, v28, v147 row_newbcast:15 row_mask:0xf bank_mask:0xf
	v_fmac_f32_dpp v11, v32, v147 row_newbcast:15 row_mask:0xf bank_mask:0xf
	v_fmac_f32_dpp v8, v36, v147 row_newbcast:15 row_mask:0xf bank_mask:0xf
	v_fmac_f32_dpp v9, v40, v147 row_newbcast:15 row_mask:0xf bank_mask:0xf
	v_fmac_f32_dpp v22, v44, v147 row_newbcast:15 row_mask:0xf bank_mask:0xf
	s_waitcnt vmcnt(47)
	v_fmac_f32_dpp v10, v29, v148 row_newbcast:0 row_mask:0xf bank_mask:0xf
	v_fmac_f32_dpp v11, v33, v148 row_newbcast:0 row_mask:0xf bank_mask:0xf
	v_fmac_f32_dpp v8, v37, v148 row_newbcast:0 row_mask:0xf bank_mask:0xf
	v_fmac_f32_dpp v9, v41, v148 row_newbcast:0 row_mask:0xf bank_mask:0xf
	v_fmac_f32_dpp v22, v45, v148 row_newbcast:0 row_mask:0xf bank_mask:0xf
	s_waitcnt vmcnt(46)
	v_fmac_f32_dpp v10, v29, v149 row_newbcast:1 row_mask:0xf bank_mask:0xf
	v_fmac_f32_dpp v11, v33, v149 row_newbcast:1 row_mask:0xf bank_mask:0xf
	v_fmac_f32_dpp v8, v37, v149 row_newbcast:1 row_mask:0xf bank_mask:0xf
	v_fmac_f32_dpp v9, v41, v149 row_newbcast:1 row_mask:0xf bank_mask:0xf
	v_fmac_f32_dpp v22, v45, v149 row_newbcast:1 row_mask:0xf bank_mask:0xf
	s_waitcnt vmcnt(45)
	v_fmac_f32_dpp v10, v29, v150 row_newbcast:2 row_mask:0xf bank_mask:0xf
	v_fmac_f32_dpp v11, v33, v150 row_newbcast:2 row_mask:0xf bank_mask:0xf
	v_fmac_f32_dpp v8, v37, v150 row_newbcast:2 row_mask:0xf bank_mask:0xf
	v_fmac_f32_dpp v9, v41, v150 row_newbcast:2 row_mask:0xf bank_mask:0xf
	v_fmac_f32_dpp v22, v45, v150 row_newbcast:2 row_mask:0xf bank_mask:0xf
	s_waitcnt vmcnt(44)
	v_fmac_f32_dpp v10, v29, v151 row_newbcast:3 row_mask:0xf bank_mask:0xf
	v_fmac_f32_dpp v11, v33, v151 row_newbcast:3 row_mask:0xf bank_mask:0xf
	v_fmac_f32_dpp v8, v37, v151 row_newbcast:3 row_mask:0xf bank_mask:0xf
	v_fmac_f32_dpp v9, v41, v151 row_newbcast:3 row_mask:0xf bank_mask:0xf
	v_fmac_f32_dpp v22, v45, v151 row_newbcast:3 row_mask:0xf bank_mask:0xf
	s_waitcnt vmcnt(43)
	v_fmac_f32_dpp v10, v29, v152 row_newbcast:4 row_mask:0xf bank_mask:0xf
	v_fmac_f32_dpp v11, v33, v152 row_newbcast:4 row_mask:0xf bank_mask:0xf
	v_fmac_f32_dpp v8, v37, v152 row_newbcast:4 row_mask:0xf bank_mask:0xf
	v_fmac_f32_dpp v9, v41, v152 row_newbcast:4 row_mask:0xf bank_mask:0xf
	v_fmac_f32_dpp v22, v45, v152 row_newbcast:4 row_mask:0xf bank_mask:0xf
	s_waitcnt vmcnt(42)
	v_fmac_f32_dpp v10, v29, v153 row_newbcast:5 row_mask:0xf bank_mask:0xf
	v_fmac_f32_dpp v11, v33, v153 row_newbcast:5 row_mask:0xf bank_mask:0xf
	v_fmac_f32_dpp v8, v37, v153 row_newbcast:5 row_mask:0xf bank_mask:0xf
	v_fmac_f32_dpp v9, v41, v153 row_newbcast:5 row_mask:0xf bank_mask:0xf
	v_fmac_f32_dpp v22, v45, v153 row_newbcast:5 row_mask:0xf bank_mask:0xf
	s_waitcnt vmcnt(41)
	v_fmac_f32_dpp v10, v29, v154 row_newbcast:6 row_mask:0xf bank_mask:0xf
	v_fmac_f32_dpp v11, v33, v154 row_newbcast:6 row_mask:0xf bank_mask:0xf
	v_fmac_f32_dpp v8, v37, v154 row_newbcast:6 row_mask:0xf bank_mask:0xf
	v_fmac_f32_dpp v9, v41, v154 row_newbcast:6 row_mask:0xf bank_mask:0xf
	v_fmac_f32_dpp v22, v45, v154 row_newbcast:6 row_mask:0xf bank_mask:0xf
	s_waitcnt vmcnt(40)
	v_fmac_f32_dpp v10, v29, v155 row_newbcast:7 row_mask:0xf bank_mask:0xf
	v_fmac_f32_dpp v11, v33, v155 row_newbcast:7 row_mask:0xf bank_mask:0xf
	v_fmac_f32_dpp v8, v37, v155 row_newbcast:7 row_mask:0xf bank_mask:0xf
	v_fmac_f32_dpp v9, v41, v155 row_newbcast:7 row_mask:0xf bank_mask:0xf
	v_fmac_f32_dpp v22, v45, v155 row_newbcast:7 row_mask:0xf bank_mask:0xf
	s_waitcnt vmcnt(39)
	v_fmac_f32_dpp v10, v29, v156 row_newbcast:8 row_mask:0xf bank_mask:0xf
	v_fmac_f32_dpp v11, v33, v156 row_newbcast:8 row_mask:0xf bank_mask:0xf
	v_fmac_f32_dpp v8, v37, v156 row_newbcast:8 row_mask:0xf bank_mask:0xf
	v_fmac_f32_dpp v9, v41, v156 row_newbcast:8 row_mask:0xf bank_mask:0xf
	v_fmac_f32_dpp v22, v45, v156 row_newbcast:8 row_mask:0xf bank_mask:0xf
	s_waitcnt vmcnt(38)
	v_fmac_f32_dpp v10, v29, v157 row_newbcast:9 row_mask:0xf bank_mask:0xf
	v_fmac_f32_dpp v11, v33, v157 row_newbcast:9 row_mask:0xf bank_mask:0xf
	v_fmac_f32_dpp v8, v37, v157 row_newbcast:9 row_mask:0xf bank_mask:0xf
	v_fmac_f32_dpp v9, v41, v157 row_newbcast:9 row_mask:0xf bank_mask:0xf
	v_fmac_f32_dpp v22, v45, v157 row_newbcast:9 row_mask:0xf bank_mask:0xf
	s_waitcnt vmcnt(37)
	v_fmac_f32_dpp v10, v29, v158 row_newbcast:10 row_mask:0xf bank_mask:0xf
	v_fmac_f32_dpp v11, v33, v158 row_newbcast:10 row_mask:0xf bank_mask:0xf
	v_fmac_f32_dpp v8, v37, v158 row_newbcast:10 row_mask:0xf bank_mask:0xf
	v_fmac_f32_dpp v9, v41, v158 row_newbcast:10 row_mask:0xf bank_mask:0xf
	v_fmac_f32_dpp v22, v45, v158 row_newbcast:10 row_mask:0xf bank_mask:0xf
	s_waitcnt vmcnt(36)
	v_fmac_f32_dpp v10, v29, v159 row_newbcast:11 row_mask:0xf bank_mask:0xf
	v_fmac_f32_dpp v11, v33, v159 row_newbcast:11 row_mask:0xf bank_mask:0xf
	v_fmac_f32_dpp v8, v37, v159 row_newbcast:11 row_mask:0xf bank_mask:0xf
	v_fmac_f32_dpp v9, v41, v159 row_newbcast:11 row_mask:0xf bank_mask:0xf
	v_fmac_f32_dpp v22, v45, v159 row_newbcast:11 row_mask:0xf bank_mask:0xf
	s_waitcnt vmcnt(35)
	v_fmac_f32_dpp v10, v29, v160 row_newbcast:12 row_mask:0xf bank_mask:0xf
	v_fmac_f32_dpp v11, v33, v160 row_newbcast:12 row_mask:0xf bank_mask:0xf
	v_fmac_f32_dpp v8, v37, v160 row_newbcast:12 row_mask:0xf bank_mask:0xf
	v_fmac_f32_dpp v9, v41, v160 row_newbcast:12 row_mask:0xf bank_mask:0xf
	v_fmac_f32_dpp v22, v45, v160 row_newbcast:12 row_mask:0xf bank_mask:0xf
	s_waitcnt vmcnt(34)
	v_fmac_f32_dpp v10, v29, v161 row_newbcast:13 row_mask:0xf bank_mask:0xf
	v_fmac_f32_dpp v11, v33, v161 row_newbcast:13 row_mask:0xf bank_mask:0xf
	v_fmac_f32_dpp v8, v37, v161 row_newbcast:13 row_mask:0xf bank_mask:0xf
	v_fmac_f32_dpp v9, v41, v161 row_newbcast:13 row_mask:0xf bank_mask:0xf
	v_fmac_f32_dpp v22, v45, v161 row_newbcast:13 row_mask:0xf bank_mask:0xf
	s_waitcnt vmcnt(33)
	v_fmac_f32_dpp v10, v29, v162 row_newbcast:14 row_mask:0xf bank_mask:0xf
	v_fmac_f32_dpp v11, v33, v162 row_newbcast:14 row_mask:0xf bank_mask:0xf
	v_fmac_f32_dpp v8, v37, v162 row_newbcast:14 row_mask:0xf bank_mask:0xf
	v_fmac_f32_dpp v9, v41, v162 row_newbcast:14 row_mask:0xf bank_mask:0xf
	v_fmac_f32_dpp v22, v45, v162 row_newbcast:14 row_mask:0xf bank_mask:0xf
	s_waitcnt vmcnt(32)
	v_fmac_f32_dpp v10, v29, v163 row_newbcast:15 row_mask:0xf bank_mask:0xf
	v_fmac_f32_dpp v11, v33, v163 row_newbcast:15 row_mask:0xf bank_mask:0xf
	v_fmac_f32_dpp v8, v37, v163 row_newbcast:15 row_mask:0xf bank_mask:0xf
	v_fmac_f32_dpp v9, v41, v163 row_newbcast:15 row_mask:0xf bank_mask:0xf
	v_fmac_f32_dpp v22, v45, v163 row_newbcast:15 row_mask:0xf bank_mask:0xf
	s_waitcnt vmcnt(31)
	v_fmac_f32_dpp v10, v30, v164 row_newbcast:0 row_mask:0xf bank_mask:0xf
	v_fmac_f32_dpp v11, v34, v164 row_newbcast:0 row_mask:0xf bank_mask:0xf
	v_fmac_f32_dpp v8, v38, v164 row_newbcast:0 row_mask:0xf bank_mask:0xf
	v_fmac_f32_dpp v9, v42, v164 row_newbcast:0 row_mask:0xf bank_mask:0xf
	v_fmac_f32_dpp v22, v46, v164 row_newbcast:0 row_mask:0xf bank_mask:0xf
	s_waitcnt vmcnt(30)
	v_fmac_f32_dpp v10, v30, v165 row_newbcast:1 row_mask:0xf bank_mask:0xf
	v_fmac_f32_dpp v11, v34, v165 row_newbcast:1 row_mask:0xf bank_mask:0xf
	v_fmac_f32_dpp v8, v38, v165 row_newbcast:1 row_mask:0xf bank_mask:0xf
	v_fmac_f32_dpp v9, v42, v165 row_newbcast:1 row_mask:0xf bank_mask:0xf
	v_fmac_f32_dpp v22, v46, v165 row_newbcast:1 row_mask:0xf bank_mask:0xf
	s_waitcnt vmcnt(29)
	v_fmac_f32_dpp v10, v30, v166 row_newbcast:2 row_mask:0xf bank_mask:0xf
	v_fmac_f32_dpp v11, v34, v166 row_newbcast:2 row_mask:0xf bank_mask:0xf
	v_fmac_f32_dpp v8, v38, v166 row_newbcast:2 row_mask:0xf bank_mask:0xf
	v_fmac_f32_dpp v9, v42, v166 row_newbcast:2 row_mask:0xf bank_mask:0xf
	v_fmac_f32_dpp v22, v46, v166 row_newbcast:2 row_mask:0xf bank_mask:0xf
	s_waitcnt vmcnt(28)
	v_fmac_f32_dpp v10, v30, v167 row_newbcast:3 row_mask:0xf bank_mask:0xf
	v_fmac_f32_dpp v11, v34, v167 row_newbcast:3 row_mask:0xf bank_mask:0xf
	v_fmac_f32_dpp v8, v38, v167 row_newbcast:3 row_mask:0xf bank_mask:0xf
	v_fmac_f32_dpp v9, v42, v167 row_newbcast:3 row_mask:0xf bank_mask:0xf
	v_fmac_f32_dpp v22, v46, v167 row_newbcast:3 row_mask:0xf bank_mask:0xf
	s_waitcnt vmcnt(27)
	v_fmac_f32_dpp v10, v30, v168 row_newbcast:4 row_mask:0xf bank_mask:0xf
	v_fmac_f32_dpp v11, v34, v168 row_newbcast:4 row_mask:0xf bank_mask:0xf
	v_fmac_f32_dpp v8, v38, v168 row_newbcast:4 row_mask:0xf bank_mask:0xf
	v_fmac_f32_dpp v9, v42, v168 row_newbcast:4 row_mask:0xf bank_mask:0xf
	v_fmac_f32_dpp v22, v46, v168 row_newbcast:4 row_mask:0xf bank_mask:0xf
	s_waitcnt vmcnt(26)
	v_fmac_f32_dpp v10, v30, v169 row_newbcast:5 row_mask:0xf bank_mask:0xf
	v_fmac_f32_dpp v11, v34, v169 row_newbcast:5 row_mask:0xf bank_mask:0xf
	v_fmac_f32_dpp v8, v38, v169 row_newbcast:5 row_mask:0xf bank_mask:0xf
	v_fmac_f32_dpp v9, v42, v169 row_newbcast:5 row_mask:0xf bank_mask:0xf
	v_fmac_f32_dpp v22, v46, v169 row_newbcast:5 row_mask:0xf bank_mask:0xf
	s_waitcnt vmcnt(25)
	v_fmac_f32_dpp v10, v30, v170 row_newbcast:6 row_mask:0xf bank_mask:0xf
	v_fmac_f32_dpp v11, v34, v170 row_newbcast:6 row_mask:0xf bank_mask:0xf
	v_fmac_f32_dpp v8, v38, v170 row_newbcast:6 row_mask:0xf bank_mask:0xf
	v_fmac_f32_dpp v9, v42, v170 row_newbcast:6 row_mask:0xf bank_mask:0xf
	v_fmac_f32_dpp v22, v46, v170 row_newbcast:6 row_mask:0xf bank_mask:0xf
	s_waitcnt vmcnt(24)
	v_fmac_f32_dpp v10, v30, v171 row_newbcast:7 row_mask:0xf bank_mask:0xf
	v_fmac_f32_dpp v11, v34, v171 row_newbcast:7 row_mask:0xf bank_mask:0xf
	v_fmac_f32_dpp v8, v38, v171 row_newbcast:7 row_mask:0xf bank_mask:0xf
	v_fmac_f32_dpp v9, v42, v171 row_newbcast:7 row_mask:0xf bank_mask:0xf
	v_fmac_f32_dpp v22, v46, v171 row_newbcast:7 row_mask:0xf bank_mask:0xf
	s_waitcnt vmcnt(23)
	v_fmac_f32_dpp v10, v30, v172 row_newbcast:8 row_mask:0xf bank_mask:0xf
	v_fmac_f32_dpp v11, v34, v172 row_newbcast:8 row_mask:0xf bank_mask:0xf
	v_fmac_f32_dpp v8, v38, v172 row_newbcast:8 row_mask:0xf bank_mask:0xf
	v_fmac_f32_dpp v9, v42, v172 row_newbcast:8 row_mask:0xf bank_mask:0xf
	v_fmac_f32_dpp v22, v46, v172 row_newbcast:8 row_mask:0xf bank_mask:0xf
	s_waitcnt vmcnt(22)
	v_fmac_f32_dpp v10, v30, v173 row_newbcast:9 row_mask:0xf bank_mask:0xf
	v_fmac_f32_dpp v11, v34, v173 row_newbcast:9 row_mask:0xf bank_mask:0xf
	v_fmac_f32_dpp v8, v38, v173 row_newbcast:9 row_mask:0xf bank_mask:0xf
	v_fmac_f32_dpp v9, v42, v173 row_newbcast:9 row_mask:0xf bank_mask:0xf
	v_fmac_f32_dpp v22, v46, v173 row_newbcast:9 row_mask:0xf bank_mask:0xf
	s_waitcnt vmcnt(21)
	v_fmac_f32_dpp v10, v30, v174 row_newbcast:10 row_mask:0xf bank_mask:0xf
	v_fmac_f32_dpp v11, v34, v174 row_newbcast:10 row_mask:0xf bank_mask:0xf
	v_fmac_f32_dpp v8, v38, v174 row_newbcast:10 row_mask:0xf bank_mask:0xf
	v_fmac_f32_dpp v9, v42, v174 row_newbcast:10 row_mask:0xf bank_mask:0xf
	v_fmac_f32_dpp v22, v46, v174 row_newbcast:10 row_mask:0xf bank_mask:0xf
	s_waitcnt vmcnt(20)
	v_fmac_f32_dpp v10, v30, v175 row_newbcast:11 row_mask:0xf bank_mask:0xf
	v_fmac_f32_dpp v11, v34, v175 row_newbcast:11 row_mask:0xf bank_mask:0xf
	v_fmac_f32_dpp v8, v38, v175 row_newbcast:11 row_mask:0xf bank_mask:0xf
	v_fmac_f32_dpp v9, v42, v175 row_newbcast:11 row_mask:0xf bank_mask:0xf
	v_fmac_f32_dpp v22, v46, v175 row_newbcast:11 row_mask:0xf bank_mask:0xf
	s_waitcnt vmcnt(19)
	v_fmac_f32_dpp v10, v30, v176 row_newbcast:12 row_mask:0xf bank_mask:0xf
	v_fmac_f32_dpp v11, v34, v176 row_newbcast:12 row_mask:0xf bank_mask:0xf
	v_fmac_f32_dpp v8, v38, v176 row_newbcast:12 row_mask:0xf bank_mask:0xf
	v_fmac_f32_dpp v9, v42, v176 row_newbcast:12 row_mask:0xf bank_mask:0xf
	v_fmac_f32_dpp v22, v46, v176 row_newbcast:12 row_mask:0xf bank_mask:0xf
	s_waitcnt vmcnt(18)
	v_fmac_f32_dpp v10, v30, v177 row_newbcast:13 row_mask:0xf bank_mask:0xf
	v_fmac_f32_dpp v11, v34, v177 row_newbcast:13 row_mask:0xf bank_mask:0xf
	v_fmac_f32_dpp v8, v38, v177 row_newbcast:13 row_mask:0xf bank_mask:0xf
	v_fmac_f32_dpp v9, v42, v177 row_newbcast:13 row_mask:0xf bank_mask:0xf
	v_fmac_f32_dpp v22, v46, v177 row_newbcast:13 row_mask:0xf bank_mask:0xf
	s_waitcnt vmcnt(17)
	v_fmac_f32_dpp v10, v30, v178 row_newbcast:14 row_mask:0xf bank_mask:0xf
	v_fmac_f32_dpp v11, v34, v178 row_newbcast:14 row_mask:0xf bank_mask:0xf
	v_fmac_f32_dpp v8, v38, v178 row_newbcast:14 row_mask:0xf bank_mask:0xf
	v_fmac_f32_dpp v9, v42, v178 row_newbcast:14 row_mask:0xf bank_mask:0xf
	v_fmac_f32_dpp v22, v46, v178 row_newbcast:14 row_mask:0xf bank_mask:0xf
	s_waitcnt vmcnt(16)
	v_fmac_f32_dpp v10, v30, v179 row_newbcast:15 row_mask:0xf bank_mask:0xf
	v_fmac_f32_dpp v11, v34, v179 row_newbcast:15 row_mask:0xf bank_mask:0xf
	v_fmac_f32_dpp v8, v38, v179 row_newbcast:15 row_mask:0xf bank_mask:0xf
	v_fmac_f32_dpp v9, v42, v179 row_newbcast:15 row_mask:0xf bank_mask:0xf
	v_fmac_f32_dpp v22, v46, v179 row_newbcast:15 row_mask:0xf bank_mask:0xf
	s_waitcnt vmcnt(15)
	v_fmac_f32_dpp v10, v31, v180 row_newbcast:0 row_mask:0xf bank_mask:0xf
	v_fmac_f32_dpp v11, v35, v180 row_newbcast:0 row_mask:0xf bank_mask:0xf
	v_fmac_f32_dpp v8, v39, v180 row_newbcast:0 row_mask:0xf bank_mask:0xf
	v_fmac_f32_dpp v9, v43, v180 row_newbcast:0 row_mask:0xf bank_mask:0xf
	v_fmac_f32_dpp v22, v47, v180 row_newbcast:0 row_mask:0xf bank_mask:0xf
	s_waitcnt vmcnt(14)
	v_fmac_f32_dpp v10, v31, v181 row_newbcast:1 row_mask:0xf bank_mask:0xf
	v_fmac_f32_dpp v11, v35, v181 row_newbcast:1 row_mask:0xf bank_mask:0xf
	v_fmac_f32_dpp v8, v39, v181 row_newbcast:1 row_mask:0xf bank_mask:0xf
	v_fmac_f32_dpp v9, v43, v181 row_newbcast:1 row_mask:0xf bank_mask:0xf
	v_fmac_f32_dpp v22, v47, v181 row_newbcast:1 row_mask:0xf bank_mask:0xf
	s_waitcnt vmcnt(13)
	v_fmac_f32_dpp v10, v31, v182 row_newbcast:2 row_mask:0xf bank_mask:0xf
	v_fmac_f32_dpp v11, v35, v182 row_newbcast:2 row_mask:0xf bank_mask:0xf
	v_fmac_f32_dpp v8, v39, v182 row_newbcast:2 row_mask:0xf bank_mask:0xf
	v_fmac_f32_dpp v9, v43, v182 row_newbcast:2 row_mask:0xf bank_mask:0xf
	v_fmac_f32_dpp v22, v47, v182 row_newbcast:2 row_mask:0xf bank_mask:0xf
	s_waitcnt vmcnt(12)
	v_fmac_f32_dpp v10, v31, v183 row_newbcast:3 row_mask:0xf bank_mask:0xf
	v_fmac_f32_dpp v11, v35, v183 row_newbcast:3 row_mask:0xf bank_mask:0xf
	v_fmac_f32_dpp v8, v39, v183 row_newbcast:3 row_mask:0xf bank_mask:0xf
	v_fmac_f32_dpp v9, v43, v183 row_newbcast:3 row_mask:0xf bank_mask:0xf
	v_fmac_f32_dpp v22, v47, v183 row_newbcast:3 row_mask:0xf bank_mask:0xf
	s_waitcnt vmcnt(11)
	v_fmac_f32_dpp v10, v31, v184 row_newbcast:4 row_mask:0xf bank_mask:0xf
	v_fmac_f32_dpp v11, v35, v184 row_newbcast:4 row_mask:0xf bank_mask:0xf
	v_fmac_f32_dpp v8, v39, v184 row_newbcast:4 row_mask:0xf bank_mask:0xf
	v_fmac_f32_dpp v9, v43, v184 row_newbcast:4 row_mask:0xf bank_mask:0xf
	v_fmac_f32_dpp v22, v47, v184 row_newbcast:4 row_mask:0xf bank_mask:0xf
	s_waitcnt vmcnt(10)
	v_fmac_f32_dpp v10, v31, v185 row_newbcast:5 row_mask:0xf bank_mask:0xf
	v_fmac_f32_dpp v11, v35, v185 row_newbcast:5 row_mask:0xf bank_mask:0xf
	v_fmac_f32_dpp v8, v39, v185 row_newbcast:5 row_mask:0xf bank_mask:0xf
	v_fmac_f32_dpp v9, v43, v185 row_newbcast:5 row_mask:0xf bank_mask:0xf
	v_fmac_f32_dpp v22, v47, v185 row_newbcast:5 row_mask:0xf bank_mask:0xf
	s_waitcnt vmcnt(9)
	v_fmac_f32_dpp v10, v31, v186 row_newbcast:6 row_mask:0xf bank_mask:0xf
	v_fmac_f32_dpp v11, v35, v186 row_newbcast:6 row_mask:0xf bank_mask:0xf
	v_fmac_f32_dpp v8, v39, v186 row_newbcast:6 row_mask:0xf bank_mask:0xf
	v_fmac_f32_dpp v9, v43, v186 row_newbcast:6 row_mask:0xf bank_mask:0xf
	v_fmac_f32_dpp v22, v47, v186 row_newbcast:6 row_mask:0xf bank_mask:0xf
	s_waitcnt vmcnt(8)
	v_fmac_f32_dpp v10, v31, v187 row_newbcast:7 row_mask:0xf bank_mask:0xf
	v_fmac_f32_dpp v11, v35, v187 row_newbcast:7 row_mask:0xf bank_mask:0xf
	v_fmac_f32_dpp v8, v39, v187 row_newbcast:7 row_mask:0xf bank_mask:0xf
	v_fmac_f32_dpp v9, v43, v187 row_newbcast:7 row_mask:0xf bank_mask:0xf
	v_fmac_f32_dpp v22, v47, v187 row_newbcast:7 row_mask:0xf bank_mask:0xf
	s_waitcnt vmcnt(7)
	v_fmac_f32_dpp v10, v31, v188 row_newbcast:8 row_mask:0xf bank_mask:0xf
	v_fmac_f32_dpp v11, v35, v188 row_newbcast:8 row_mask:0xf bank_mask:0xf
	v_fmac_f32_dpp v8, v39, v188 row_newbcast:8 row_mask:0xf bank_mask:0xf
	v_fmac_f32_dpp v9, v43, v188 row_newbcast:8 row_mask:0xf bank_mask:0xf
	v_fmac_f32_dpp v22, v47, v188 row_newbcast:8 row_mask:0xf bank_mask:0xf
	s_waitcnt vmcnt(6)
	v_fmac_f32_dpp v10, v31, v189 row_newbcast:9 row_mask:0xf bank_mask:0xf
	v_fmac_f32_dpp v11, v35, v189 row_newbcast:9 row_mask:0xf bank_mask:0xf
	v_fmac_f32_dpp v8, v39, v189 row_newbcast:9 row_mask:0xf bank_mask:0xf
	v_fmac_f32_dpp v9, v43, v189 row_newbcast:9 row_mask:0xf bank_mask:0xf
	v_fmac_f32_dpp v22, v47, v189 row_newbcast:9 row_mask:0xf bank_mask:0xf
	s_waitcnt vmcnt(5)
	v_fmac_f32_dpp v10, v31, v190 row_newbcast:10 row_mask:0xf bank_mask:0xf
	v_fmac_f32_dpp v11, v35, v190 row_newbcast:10 row_mask:0xf bank_mask:0xf
	v_fmac_f32_dpp v8, v39, v190 row_newbcast:10 row_mask:0xf bank_mask:0xf
	v_fmac_f32_dpp v9, v43, v190 row_newbcast:10 row_mask:0xf bank_mask:0xf
	v_fmac_f32_dpp v22, v47, v190 row_newbcast:10 row_mask:0xf bank_mask:0xf
	s_waitcnt vmcnt(4)
	v_fmac_f32_dpp v10, v31, v191 row_newbcast:11 row_mask:0xf bank_mask:0xf
	v_fmac_f32_dpp v11, v35, v191 row_newbcast:11 row_mask:0xf bank_mask:0xf
	v_fmac_f32_dpp v8, v39, v191 row_newbcast:11 row_mask:0xf bank_mask:0xf
	v_fmac_f32_dpp v9, v43, v191 row_newbcast:11 row_mask:0xf bank_mask:0xf
	v_fmac_f32_dpp v22, v47, v191 row_newbcast:11 row_mask:0xf bank_mask:0xf
	s_waitcnt vmcnt(3)
	v_fmac_f32_dpp v10, v31, v192 row_newbcast:12 row_mask:0xf bank_mask:0xf
	v_fmac_f32_dpp v11, v35, v192 row_newbcast:12 row_mask:0xf bank_mask:0xf
	v_fmac_f32_dpp v8, v39, v192 row_newbcast:12 row_mask:0xf bank_mask:0xf
	v_fmac_f32_dpp v9, v43, v192 row_newbcast:12 row_mask:0xf bank_mask:0xf
	v_fmac_f32_dpp v22, v47, v192 row_newbcast:12 row_mask:0xf bank_mask:0xf
	s_waitcnt vmcnt(2)
	v_fmac_f32_dpp v10, v31, v193 row_newbcast:13 row_mask:0xf bank_mask:0xf
	v_fmac_f32_dpp v11, v35, v193 row_newbcast:13 row_mask:0xf bank_mask:0xf
	v_fmac_f32_dpp v8, v39, v193 row_newbcast:13 row_mask:0xf bank_mask:0xf
	v_fmac_f32_dpp v9, v43, v193 row_newbcast:13 row_mask:0xf bank_mask:0xf
	v_fmac_f32_dpp v22, v47, v193 row_newbcast:13 row_mask:0xf bank_mask:0xf
	s_waitcnt vmcnt(1)
	v_fmac_f32_dpp v10, v31, v194 row_newbcast:14 row_mask:0xf bank_mask:0xf
	v_fmac_f32_dpp v11, v35, v194 row_newbcast:14 row_mask:0xf bank_mask:0xf
	v_fmac_f32_dpp v8, v39, v194 row_newbcast:14 row_mask:0xf bank_mask:0xf
	v_fmac_f32_dpp v9, v43, v194 row_newbcast:14 row_mask:0xf bank_mask:0xf
	v_fmac_f32_dpp v22, v47, v194 row_newbcast:14 row_mask:0xf bank_mask:0xf
	s_waitcnt vmcnt(0)
	v_fmac_f32_dpp v10, v31, v195 row_newbcast:15 row_mask:0xf bank_mask:0xf
	v_fmac_f32_dpp v11, v35, v195 row_newbcast:15 row_mask:0xf bank_mask:0xf
	v_fmac_f32_dpp v8, v39, v195 row_newbcast:15 row_mask:0xf bank_mask:0xf
	v_fmac_f32_dpp v9, v43, v195 row_newbcast:15 row_mask:0xf bank_mask:0xf
	v_fmac_f32_dpp v22, v47, v195 row_newbcast:15 row_mask:0xf bank_mask:0xf
	s_mov_b32 s70, 64
	s_mov_b64 s[8:9], 0
	s_and_b64 vcc, exec, s[6:7]
	s_cbranch_vccz .LBB0_20
	v_lshlrev_b32_e32 v0, 3, v17
	v_and_b32_e32 v6, 0xffffffc0, v0
	v_ashrrev_i32_e32 v7, 31, v6
	v_lshl_add_u64 v[6:7], v[6:7], 2, v[2:3]
	v_add_co_u32_e32 v12, vcc, 0x3000, v6
	global_store_dword v[6:7], v10, off
	s_nop 0
	v_addc_co_u32_e32 v13, vcc, 0, v7, vcc
	v_add_co_u32_e32 v10, vcc, 0x6000, v6
	global_store_dword v[12:13], v11, off
	s_nop 0
	v_addc_co_u32_e32 v11, vcc, 0, v7, vcc
	global_store_dword v[10:11], v8, off
	v_add_co_u32_e32 v10, vcc, 0x9000, v6
	v_add_u32_e32 v17, s33, v17
	s_nop 0
	v_addc_co_u32_e32 v11, vcc, 0, v7, vcc
	v_add_co_u32_e32 v6, vcc, 0xc000, v6
	v_add_u32_e32 v19, s3, v19
	s_nop 0
	v_addc_co_u32_e32 v7, vcc, 0, v7, vcc
	v_cmp_lt_i32_e32 vcc, s69, v17
	s_or_b64 s[4:5], vcc, s[4:5]
	global_store_dword v[10:11], v9, off
	global_store_dword v[6:7], v22, off
	s_andn2_b64 exec, exec, s[4:5]
	s_cbranch_execnz .LBB0_19
